# attention-internal grid barrier: waiters also poll the arrival counter directly (all 12 barriers now)
# speedup vs baseline: 1.0098x; 1.0046x over previous
.Lattn_prio_done:
	s_load_dwordx2 s[62:63], s[0:1], 0xd0
	v_ashrrev_i32_e32 v218, 4, v0
	v_and_b32_e32 v0, 15, v0
	v_lshlrev_b32_e32 v7, 4, v0
	v_ashrrev_i32_e32 v12, 2, v243
	s_waitcnt lgkmcnt(0)
	s_add_u32 s4, s62, 0x8000000
	s_addc_u32 s5, s63, 0
	s_add_u32 s8, s62, 0xe000000
	s_addc_u32 s9, s63, 0
	s_add_i32 s12, 0, 0x11800
	v_and_b32_e32 v162, -8, v12
	v_add_u32_e32 v12, s12, v7
	s_add_i32 s12, 0, 0x15c00
	v_add_u32_e32 v13, s12, v7
	s_movk_i32 s12, 0x110
	v_and_b32_e32 v5, 15, v243
	s_and_b32 s15, s97, 32
	v_mul_lo_u32 v221, v218, s12
	s_add_i32 s12, 0, 0x1a400
	v_or_b32_e32 v219, s15, v5
	v_add_u32_e32 v14, s12, v7
	s_add_i32 s12, 0, 0x1e800
	v_and_b32_e32 v8, -16, v243
	v_add_u32_e32 v15, s12, v7
	v_add_u32_e32 v223, 0, v7
	v_mul_u32_u24_e32 v7, 0x110, v219
	s_add_i32 s13, s15, 32
	v_add3_u32 v224, 0, v7, v8
	v_and_or_b32 v7, s13, 32, v5
	v_mul_u32_u24_e32 v7, 0x110, v7
	s_add_i32 s14, s15, 48
	v_add3_u32 v225, 0, v7, v8
	v_and_or_b32 v7, s14, 48, v5
	v_mul_u32_u24_e32 v7, 0x110, v7
	s_add_i32 s16, s15, 0x60
	v_add3_u32 v226, 0, v7, v8
	v_and_or_b32 v7, s16, 32, v5
	s_bfe_u32 s11, s78, 0x10006
	s_lshr_b32 s12, s13, 6
	s_lshr_b32 s13, s14, 6
	s_lshr_b32 s14, s16, 6
	v_mul_u32_u24_e32 v7, 0x110, v7
	s_add_i32 s16, s15, 0x70
	v_add3_u32 v227, 0, v7, v8
	s_lshr_b32 s15, s16, 6
	v_and_or_b32 v7, s16, 48, v5
	s_add_i32 s16, s11, 3
	s_lshl_b32 s17, s16, 5
	s_lshr_b32 s10, s78, 7
	s_lshl_b32 s19, s11, 5
	s_lshr_b32 s16, s16, 1
	s_and_b32 s17, s17, 32
	s_add_u32 s66, s54, 0x200
	s_addc_u32 s67, s55, 0
	s_add_u32 s68, s54, 0x1000
	s_addc_u32 s69, s55, 0
	s_add_u32 s70, s54, 0x1100
	v_ashrrev_i32_e32 v1, 4, v243
	s_addc_u32 s71, s55, 0
	v_lshlrev_b32_e32 v160, 2, v1
	v_bfe_u32 v9, v243, 2, 2
	s_add_u32 s72, s54, 0x1200
	v_or_b32_e32 v10, v160, v9
	v_mul_u32_u24_e32 v7, 0x110, v7
	s_addc_u32 s73, s55, 0
	v_add3_u32 v228, 0, v7, v8
	v_add_u32_e32 v7, s19, v10
	v_xad_u32 v8, s19, 32, v10
	v_add_u32_e32 v10, s17, v10
	s_mul_i32 s17, s53, s52
	s_add_u32 s74, s54, 0x1300
	s_mul_i32 s17, s17, s75
	s_addc_u32 s75, s55, 0
	v_writelane_b32 v255, s76, 4
	s_cmp_eq_u32 s3, 15
	s_cselect_b64 s[20:21], -1, 0
	v_writelane_b32 v255, s77, 5
	v_writelane_b32 v255, s20, 2
	s_cmp_eq_u32 s3, 14
	v_and_b32_e32 v6, 3, v243
	v_writelane_b32 v255, s21, 3
	s_cselect_b64 s[20:21], -1, 0
	v_writelane_b32 v255, s20, 6
	s_cmp_eq_u32 s3, 13
	s_movk_i32 s18, 0x120
	v_writelane_b32 v255, s21, 7
	s_cselect_b64 s[20:21], -1, 0
	v_writelane_b32 v255, s20, 8
	s_cmp_eq_u32 s3, 12
	v_lshlrev_b32_e32 v11, 3, v6
	v_writelane_b32 v255, s21, 9
	s_cselect_b64 s[20:21], -1, 0
	v_writelane_b32 v255, s20, 10
	s_cmp_eq_u32 s3, 11
	v_mul_lo_u32 v7, v7, s18
	v_writelane_b32 v255, s21, 11
	s_cselect_b64 s[20:21], -1, 0
	v_writelane_b32 v255, s20, 12
	s_cmp_eq_u32 s3, 10
	v_add_u32_e32 v232, s19, v160
	v_writelane_b32 v255, s21, 13
	s_cselect_b64 s[20:21], -1, 0
	v_writelane_b32 v255, s20, 14
	s_cmp_eq_u32 s3, 9
	v_lshlrev_b32_e32 v4, 3, v0
	v_writelane_b32 v255, s21, 15
	s_cselect_b64 s[20:21], -1, 0
	v_writelane_b32 v255, s20, 16
	s_cmp_eq_u32 s3, 8
	v_mov_b32_e32 v0, 0x3f80
	v_writelane_b32 v255, s21, 17
	s_cselect_b64 s[20:21], -1, 0
	v_writelane_b32 v255, s20, 18
	s_cmp_eq_u32 s3, 7
	v_cmp_eq_u32_e32 vcc, 0, v6
	v_writelane_b32 v255, s21, 19
	s_cselect_b64 s[20:21], -1, 0
	v_writelane_b32 v255, s20, 20
	s_cmp_eq_u32 s3, 6
	v_add3_u32 v229, 0, v7, v11
	v_writelane_b32 v255, s21, 21
	s_cselect_b64 s[20:21], -1, 0
	v_writelane_b32 v255, s20, 22
	s_cmp_eq_u32 s3, 5
	v_or_b32_e32 v7, v232, v9
	v_writelane_b32 v255, s21, 23
	s_cselect_b64 s[20:21], -1, 0
	s_cmp_eq_u32 s3, 4
	s_cselect_b64 s[30:31], -1, 0
	s_cmp_eq_u32 s3, 3
	s_cselect_b64 s[34:35], -1, 0
	s_cmp_eq_u32 s3, 2
	s_cselect_b64 s[36:37], -1, 0
	s_cmp_eq_u32 s3, 1
	v_writelane_b32 v255, s20, 24
	s_cselect_b64 s[38:39], -1, 0
	s_cmp_eq_u32 s3, 0
	v_writelane_b32 v255, s21, 25
	s_cselect_b64 s[40:41], -1, 0
	s_lshl_b32 s20, s3, 8
	s_add_u32 s20, s54, s20
	s_addc_u32 s21, s55, 0
	s_add_u32 s76, s20, 0x1400
	s_addc_u32 s77, s21, 0
	s_add_u32 s78, s20, 0x2400
	s_addc_u32 s79, s21, 0
	s_add_u32 s100, s54, 0x3400
	s_addc_u32 s101, s55, 0
	s_add_u32 s80, s54, 0x3400
	v_cndmask_b32_e32 v0, 0, v0, vcc
	s_mov_b32 s6, 0x5040100
	s_addc_u32 s81, s55, 0
	v_mul_lo_u32 v7, v7, s18
	v_lshlrev_b32_e32 v158, 3, v1
	v_perm_b32 v0, v0, v0, s6
	v_and_b32_e32 v6, 16, v243
	v_mul_lo_u32 v222, v218, s18
	v_mul_lo_u32 v8, v8, s18
	v_mul_lo_u32 v10, v10, s18
	s_add_u32 s82, s54, 0x3500
	v_or_b32_e32 v7, v7, v11
	v_or_b32_e32 v234, s19, v5
	s_mov_b32 s65, 0
	v_mov_b32_e32 v157, 0
	v_ashrrev_i32_e32 v159, 31, v158
	v_sub_u32_e32 v220, v5, v160
	v_mov_b32_e32 v1, v0
	v_mov_b32_e32 v2, v0
	v_mov_b32_e32 v3, v0
	v_ashrrev_i32_e32 v161, 31, v160
	v_ashrrev_i32_e32 v163, 31, v162
	v_cmp_gt_u32_e64 s[6:7], 16, v243
	s_addc_u32 s83, s55, 0
	v_add3_u32 v230, 0, v8, v11
	v_add3_u32 v231, 0, v10, v11
	v_add_u32_e32 v233, 0, v7
	v_or_b32_e32 v235, 0x50, v234
	v_add_u32_e32 v254, 0x60, v218
	v_or_b32_e32 v238, 16, v234
	s_mov_b64 s[84:85], 0
	s_add_i32 s18, 0, 0x243c0
	s_add_i32 s19, 0, 0x243c4
	v_mov_b32_e32 v239, 0xc2000
	s_movk_i32 s20, 0x1800
	v_lshlrev_b32_e32 v164, 1, v4
	s_movk_i32 s21, 0xc00
	v_add_u32_e32 v240, v12, v221
	v_add_u32_e32 v241, v13, v222
	v_add_u32_e32 v243, v14, v221
	v_add_u32_e32 v244, v15, v222
	v_lshlrev_b32_e32 v166, 1, v6
	s_mov_b32 s22, 0x3f317218
	v_mov_b32_e32 v245, 0xff61b1e6
	s_branch .LBB0_901

.LBB0_920:
	s_or_b64 exec, exec, s[48:49]
	v_cvt_f32_u32_e32 v56, v54
	s_waitcnt vmcnt(0)
	v_readfirstlane_b32 s23, v55
	v_sub_u32_e32 v55, 0, v54
	v_rcp_iflag_f32_e32 v56, v56
	v_add_u32_e32 v57, s23, v53
	v_mul_f32_e32 v56, 0x4f7ffffe, v56
	v_cvt_u32_f32_e32 v56, v56
	v_mul_lo_u32 v53, v55, v56
	v_mul_hi_u32 v53, v56, v53
	v_add_u32_e32 v53, v56, v53
	v_mul_hi_u32 v53, v57, v53
	v_mul_lo_u32 v55, v53, v54
	v_sub_u32_e32 v55, v57, v55
	v_add_u32_e32 v56, 1, v53
	v_cmp_ge_u32_e32 vcc, v55, v54
	s_nop 1
	v_cndmask_b32_e32 v53, v53, v56, vcc
	v_sub_u32_e32 v56, v55, v54
	v_cndmask_b32_e32 v55, v55, v56, vcc
	v_add_u32_e32 v56, 1, v53
	v_cmp_ge_u32_e32 vcc, v55, v54
	v_add_u32_e32 v55, 1, v57
	s_nop 0
	v_cndmask_b32_e32 v53, v53, v56, vcc
	v_mul_lo_u32 v56, v54, v53
	v_add_u32_e32 v54, v56, v54
	v_cmp_ne_u32_e32 vcc, v55, v54
	s_and_saveexec_b64 s[24:25], vcc
	s_xor_b64 s[48:49], exec, s[24:25]
	s_cbranch_execz .LBB0_934
	s_waitcnt lgkmcnt(0)
	v_mad_u32_u24 v56, v53, v52, v52
	global_load_dword v52, v157, s[100:101] sc1
	s_waitcnt vmcnt(0)
	v_cmp_lt_u32_e32 vcc, v52, v56
	s_and_saveexec_b64 s[50:51], vcc
	s_cbranch_execz .LBB0_933
	s_mov_b32 s23, 1
	s_mov_b64 s[84:85], 0
	s_branch .LBB0_924

.LBB0_928:
	global_load_dword v52, v157, s[100:101] sc1
	s_add_i32 s23, s23, 1
	s_mov_b64 s[90:91], -1
	s_waitcnt vmcnt(0)
	v_cmp_ge_u32_e32 vcc, v52, v56
	s_orn2_b64 s[88:89], vcc, exec
	s_branch .LBB0_923

.LBB0_937:
	s_or_b64 exec, exec, s[50:51]
	s_waitcnt vmcnt(0)
	v_readfirstlane_b32 s23, v54
	v_cvt_f32_u32_e32 v54, v52
	v_sub_u32_e32 v55, 0, v52
	v_add_u32_e32 v53, s23, v53
	s_mov_b64 s[50:51], -1
	v_rcp_iflag_f32_e32 v54, v54
	s_nop 0
	v_mul_f32_e32 v54, 0x4f7ffffe, v54
	v_cvt_u32_f32_e32 v54, v54
	v_mul_lo_u32 v55, v55, v54
	v_mul_hi_u32 v55, v54, v55
	v_add_u32_e32 v54, v54, v55
	v_mul_hi_u32 v54, v53, v54
	v_mul_lo_u32 v55, v54, v52
	v_sub_u32_e32 v55, v53, v55
	v_cmp_ge_u32_e32 vcc, v55, v52
	v_add_u32_e32 v56, 1, v54
	v_add_u32_e32 v53, 1, v53
	v_cndmask_b32_e32 v54, v54, v56, vcc
	v_sub_u32_e32 v56, v55, v52
	v_cndmask_b32_e32 v55, v55, v56, vcc
	v_cmp_ge_u32_e32 vcc, v55, v52
	v_add_u32_e32 v55, 1, v54
	s_nop 0
	v_cndmask_b32_e32 v54, v54, v55, vcc
	v_mul_lo_u32 v55, v52, v54
	v_add_u32_e32 v52, v55, v52
	v_cmp_ne_u32_e32 vcc, v53, v52
	v_mov_b32_e32 v56, v52
	v_mov_b64_e32 v[52:53], s[82:83]
	s_and_saveexec_b64 s[48:49], vcc
	s_cbranch_execz .LBB0_949
	global_load_dword v52, v157, s[82:83] offset:-256 sc1
	s_mov_b64 s[60:61], 0
	s_waitcnt vmcnt(0)
	v_cmp_lt_u32_e32 vcc, v52, v56
	s_and_saveexec_b64 s[50:51], vcc
	s_cbranch_execz .LBB0_948
	s_mov_b32 s23, 1
	s_mov_b64 s[84:85], 0
	s_branch .LBB0_941

.LBB0_945:
	global_load_dword v52, v157, s[82:83] offset:-256 sc1
	s_add_i32 s23, s23, 1
	s_mov_b64 s[90:91], -1
	s_waitcnt vmcnt(0)
	v_cmp_ge_u32_e32 vcc, v52, v56
	s_orn2_b64 s[88:89], vcc, exec
	s_branch .LBB0_940

.Lph1109_w:
	s_nop 0
	s_nop 0
	s_nop 0
	s_nop 0
	s_nop 0
	s_waitcnt vmcnt(8)
	s_waitcnt lgkmcnt(0)
	s_setprio 1
	s_barrier
	v_mfma_f32_16x16x32_bf16 v[144:147], v[120:123], v[160:163], v[144:147]
	v_mfma_f32_16x16x32_bf16 v[136:139], v[128:131], v[160:163], v[136:139]
	v_mfma_f32_16x16x32_bf16 v[108:111], v[120:123], v[168:171], v[108:111]
	v_mfma_f32_16x16x32_bf16 v[104:107], v[128:131], v[168:171], v[104:107]
	v_mfma_f32_16x16x32_bf16 v[92:95], v[120:123], v[176:179], v[92:95]
	v_mfma_f32_16x16x32_bf16 v[88:91], v[128:131], v[176:179], v[88:91]
	v_mfma_f32_16x16x32_bf16 v[76:79], v[120:123], v[184:187], v[76:79]
	v_mfma_f32_16x16x32_bf16 v[72:75], v[128:131], v[184:187], v[72:75]
	v_mfma_f32_16x16x32_bf16 v[144:147], v[124:127], v[164:167], v[144:147]
	v_mfma_f32_16x16x32_bf16 v[136:139], v[132:135], v[164:167], v[136:139]
	v_mfma_f32_16x16x32_bf16 v[108:111], v[124:127], v[172:175], v[108:111]
	v_mfma_f32_16x16x32_bf16 v[104:107], v[132:135], v[172:175], v[104:107]
	v_mfma_f32_16x16x32_bf16 v[92:95], v[124:127], v[180:183], v[92:95]
	v_mfma_f32_16x16x32_bf16 v[88:91], v[132:135], v[180:183], v[88:91]
	v_mfma_f32_16x16x32_bf16 v[76:79], v[124:127], v[188:191], v[76:79]
	v_mfma_f32_16x16x32_bf16 v[72:75], v[132:135], v[188:191], v[72:75]
	s_setprio 0
	s_setprio 1
	v_mfma_f32_16x16x32_bf16 v[116:119], v[140:143], v[160:163], v[116:119]
	v_mfma_f32_16x16x32_bf16 v[112:115], v[152:155], v[160:163], v[112:115]
	v_mfma_f32_16x16x32_bf16 v[100:103], v[140:143], v[168:171], v[100:103]
	v_mfma_f32_16x16x32_bf16 v[96:99], v[152:155], v[168:171], v[96:99]
	v_mfma_f32_16x16x32_bf16 v[84:87], v[140:143], v[176:179], v[84:87]
	v_mfma_f32_16x16x32_bf16 v[80:83], v[152:155], v[176:179], v[80:83]
	v_mfma_f32_16x16x32_bf16 v[68:71], v[140:143], v[184:187], v[68:71]
	v_mfma_f32_16x16x32_bf16 v[64:67], v[152:155], v[184:187], v[64:67]
	v_mfma_f32_16x16x32_bf16 v[116:119], v[148:151], v[164:167], v[116:119]
	v_mfma_f32_16x16x32_bf16 v[112:115], v[156:159], v[164:167], v[112:115]
	v_mfma_f32_16x16x32_bf16 v[100:103], v[148:151], v[172:175], v[100:103]
	v_mfma_f32_16x16x32_bf16 v[96:99], v[156:159], v[172:175], v[96:99]
	v_mfma_f32_16x16x32_bf16 v[84:87], v[148:151], v[180:183], v[84:87]
	v_mfma_f32_16x16x32_bf16 v[80:83], v[156:159], v[180:183], v[80:83]
	v_mfma_f32_16x16x32_bf16 v[68:71], v[148:151], v[188:191], v[68:71]
	v_mfma_f32_16x16x32_bf16 v[64:67], v[156:159], v[188:191], v[64:67]
	s_barrier
	s_setprio 0
	s_add_i32 s65, s51, s37
	v_lshl_add_u64 v[206:207], s[30:31], 0, v[194:195]
	s_mov_b32 m0, s65
	s_nop 0
	global_load_lds_dwordx4 v[206:207], off
	s_add_i32 m0, s65, 0x2000
	s_add_u32 s66, s30, 0x40000
	v_lshl_add_u64 v[208:209], s[30:31], 0, v[198:199]
	s_addc_u32 s67, s31, 0
	s_add_i32 s65, s60, s37
	global_load_lds_dwordx4 v[208:209], off
	v_lshl_add_u64 v[210:211], s[66:67], 0, v[194:195]
	s_mov_b32 m0, s65
	v_lshl_add_u64 v[212:213], s[34:35], 0, v[196:197]
	global_load_lds_dwordx4 v[210:211], off
	v_lshl_add_u64 v[210:211], s[66:67], 0, v[198:199]
	s_add_i32 m0, s65, 0x2000
	s_nop 0
	global_load_lds_dwordx4 v[210:211], off
	v_lshl_add_u64 v[210:211], s[34:35], 0, v[192:193]
	s_mov_b32 m0, s27
	s_nop 0
	global_load_lds_dwordx4 v[210:211], off
	s_mov_b32 m0, s38
	s_nop 0
	global_load_lds_dwordx4 v[212:213], off
	ds_read_b128 v[160:163], v248 offset:16384
	ds_read_b128 v[164:167], v248 offset:17408
	ds_read_b128 v[168:171], v248 offset:18432
	ds_read_b128 v[172:175], v248 offset:19456
	ds_read_b128 v[176:179], v248 offset:20480
	ds_read_b128 v[180:183], v248 offset:21504
	ds_read_b128 v[184:187], v248 offset:22528
	ds_read_b128 v[188:191], v248 offset:23552
	s_nop 0
	s_waitcnt vmcnt(8)
	s_waitcnt lgkmcnt(0)
	s_setprio 1
	s_barrier
	v_mfma_f32_16x16x32_bf16 v[60:63], v[120:123], v[160:163], v[60:63]
	v_mfma_f32_16x16x32_bf16 v[56:59], v[128:131], v[160:163], v[56:59]
	v_mfma_f32_16x16x32_bf16 v[44:47], v[120:123], v[168:171], v[44:47]
	v_mfma_f32_16x16x32_bf16 v[40:43], v[128:131], v[168:171], v[40:43]
	v_mfma_f32_16x16x32_bf16 v[28:31], v[120:123], v[176:179], v[28:31]
	v_mfma_f32_16x16x32_bf16 v[24:27], v[128:131], v[176:179], v[24:27]
	v_mfma_f32_16x16x32_bf16 v[12:15], v[120:123], v[184:187], v[12:15]
	v_mfma_f32_16x16x32_bf16 v[8:11], v[128:131], v[184:187], v[8:11]
	v_mfma_f32_16x16x32_bf16 v[60:63], v[124:127], v[164:167], v[60:63]
	v_mfma_f32_16x16x32_bf16 v[56:59], v[132:135], v[164:167], v[56:59]
	v_mfma_f32_16x16x32_bf16 v[44:47], v[124:127], v[172:175], v[44:47]
	v_mfma_f32_16x16x32_bf16 v[40:43], v[132:135], v[172:175], v[40:43]
	v_mfma_f32_16x16x32_bf16 v[28:31], v[124:127], v[180:183], v[28:31]
	v_mfma_f32_16x16x32_bf16 v[24:27], v[132:135], v[180:183], v[24:27]
	v_mfma_f32_16x16x32_bf16 v[12:15], v[124:127], v[188:191], v[12:15]
	v_mfma_f32_16x16x32_bf16 v[8:11], v[132:135], v[188:191], v[8:11]
	s_setprio 0
	s_setprio 1
	v_mfma_f32_16x16x32_bf16 v[52:55], v[140:143], v[160:163], v[52:55]
	v_mfma_f32_16x16x32_bf16 v[48:51], v[152:155], v[160:163], v[48:51]
	v_mfma_f32_16x16x32_bf16 v[36:39], v[140:143], v[168:171], v[36:39]
	v_mfma_f32_16x16x32_bf16 v[32:35], v[152:155], v[168:171], v[32:35]
	v_mfma_f32_16x16x32_bf16 v[20:23], v[140:143], v[176:179], v[20:23]
	v_mfma_f32_16x16x32_bf16 v[16:19], v[152:155], v[176:179], v[16:19]
	v_mfma_f32_16x16x32_bf16 v[4:7], v[140:143], v[184:187], v[4:7]
	v_mfma_f32_16x16x32_bf16 v[0:3], v[152:155], v[184:187], v[0:3]
	v_mfma_f32_16x16x32_bf16 v[52:55], v[148:151], v[164:167], v[52:55]
	v_mfma_f32_16x16x32_bf16 v[48:51], v[156:159], v[164:167], v[48:51]
	v_mfma_f32_16x16x32_bf16 v[36:39], v[148:151], v[172:175], v[36:39]
	v_mfma_f32_16x16x32_bf16 v[32:35], v[156:159], v[172:175], v[32:35]
	v_mfma_f32_16x16x32_bf16 v[20:23], v[148:151], v[180:183], v[20:23]
	v_mfma_f32_16x16x32_bf16 v[16:19], v[156:159], v[180:183], v[16:19]
	v_mfma_f32_16x16x32_bf16 v[4:7], v[148:151], v[188:191], v[4:7]
	v_mfma_f32_16x16x32_bf16 v[0:3], v[156:159], v[188:191], v[0:3]
	s_barrier
	s_setprio 0
	s_add_i32 s65, 0, 0x18000
	s_add_i32 s66, 0, 0x1c000
	s_add_u32 s34, s34, 0x40000
	s_addc_u32 s35, s35, 0
	s_mov_b32 m0, s39
	v_lshl_add_u64 v[214:215], s[34:35], 0, v[192:193]
	global_load_lds_dwordx4 v[214:215], off
	v_lshl_add_u64 v[214:215], s[34:35], 0, v[196:197]
	s_mov_b32 m0, s40
	s_nop 0
	global_load_lds_dwordx4 v[214:215], off
	v_add_u32_e32 v132, s65, v245
	v_add_u32_e32 v156, s66, v245
	ds_read_b128 v[120:123], v132
	ds_read_b128 v[124:127], v132 offset:1024
	ds_read_b128 v[128:131], v132 offset:2048
	ds_read_b128 v[132:135], v132 offset:3072
	ds_read_b128 v[140:143], v156
	ds_read_b128 v[148:151], v156 offset:1024
	ds_read_b128 v[152:155], v156 offset:2048
	ds_read_b128 v[156:159], v156 offset:3072
	ds_read_b128 v[160:163], v248 offset:32768
	ds_read_b128 v[164:167], v248 offset:33792
	ds_read_b128 v[168:171], v248 offset:34816
	ds_read_b128 v[172:175], v248 offset:35840
	ds_read_b128 v[176:179], v248 offset:36864
	ds_read_b128 v[180:183], v248 offset:37888
	ds_read_b128 v[184:187], v248 offset:38912
	ds_read_b128 v[188:191], v248 offset:39936
	s_waitcnt vmcnt(8)
	s_waitcnt lgkmcnt(0)
	s_setprio 1
	s_barrier
	v_mfma_f32_16x16x32_bf16 v[144:147], v[120:123], v[160:163], v[144:147]
	v_mfma_f32_16x16x32_bf16 v[136:139], v[128:131], v[160:163], v[136:139]
	v_mfma_f32_16x16x32_bf16 v[108:111], v[120:123], v[168:171], v[108:111]
	v_mfma_f32_16x16x32_bf16 v[104:107], v[128:131], v[168:171], v[104:107]
	v_mfma_f32_16x16x32_bf16 v[92:95], v[120:123], v[176:179], v[92:95]
	v_mfma_f32_16x16x32_bf16 v[88:91], v[128:131], v[176:179], v[88:91]
	v_mfma_f32_16x16x32_bf16 v[76:79], v[120:123], v[184:187], v[76:79]
	v_mfma_f32_16x16x32_bf16 v[72:75], v[128:131], v[184:187], v[72:75]
	v_mfma_f32_16x16x32_bf16 v[144:147], v[124:127], v[164:167], v[144:147]
	v_mfma_f32_16x16x32_bf16 v[136:139], v[132:135], v[164:167], v[136:139]
	v_mfma_f32_16x16x32_bf16 v[108:111], v[124:127], v[172:175], v[108:111]
	v_mfma_f32_16x16x32_bf16 v[104:107], v[132:135], v[172:175], v[104:107]
	v_mfma_f32_16x16x32_bf16 v[92:95], v[124:127], v[180:183], v[92:95]
	v_mfma_f32_16x16x32_bf16 v[88:91], v[132:135], v[180:183], v[88:91]
	v_mfma_f32_16x16x32_bf16 v[76:79], v[124:127], v[188:191], v[76:79]
	v_mfma_f32_16x16x32_bf16 v[72:75], v[132:135], v[188:191], v[72:75]
	s_setprio 0
	s_setprio 1
	v_mfma_f32_16x16x32_bf16 v[116:119], v[140:143], v[160:163], v[116:119]
	v_mfma_f32_16x16x32_bf16 v[112:115], v[152:155], v[160:163], v[112:115]
	v_mfma_f32_16x16x32_bf16 v[100:103], v[140:143], v[168:171], v[100:103]
	v_mfma_f32_16x16x32_bf16 v[96:99], v[152:155], v[168:171], v[96:99]
	v_mfma_f32_16x16x32_bf16 v[84:87], v[140:143], v[176:179], v[84:87]
	v_mfma_f32_16x16x32_bf16 v[80:83], v[152:155], v[176:179], v[80:83]
	v_mfma_f32_16x16x32_bf16 v[68:71], v[140:143], v[184:187], v[68:71]
	v_mfma_f32_16x16x32_bf16 v[64:67], v[152:155], v[184:187], v[64:67]
	v_mfma_f32_16x16x32_bf16 v[116:119], v[148:151], v[164:167], v[116:119]
	v_mfma_f32_16x16x32_bf16 v[112:115], v[156:159], v[164:167], v[112:115]
	v_mfma_f32_16x16x32_bf16 v[100:103], v[148:151], v[172:175], v[100:103]
	v_mfma_f32_16x16x32_bf16 v[96:99], v[156:159], v[172:175], v[96:99]
	v_mfma_f32_16x16x32_bf16 v[84:87], v[148:151], v[180:183], v[84:87]
	v_mfma_f32_16x16x32_bf16 v[80:83], v[156:159], v[180:183], v[80:83]
	v_mfma_f32_16x16x32_bf16 v[68:71], v[148:151], v[188:191], v[68:71]
	v_mfma_f32_16x16x32_bf16 v[64:67], v[156:159], v[188:191], v[64:67]
	s_barrier
	s_setprio 0
	s_add_i32 s34, s65, s37
	v_lshl_add_u64 v[206:207], v[206:207], 0, s[12:13]
	s_mov_b32 m0, s34
	s_nop 0
	global_load_lds_dwordx4 v[206:207], off
	s_add_i32 m0, s34, 0x2000
	s_add_u32 s30, s30, 0x40080
	v_lshl_add_u64 v[206:207], v[208:209], 0, s[12:13]
	s_addc_u32 s31, s31, 0
	s_add_i32 s34, s66, s37
	global_load_lds_dwordx4 v[206:207], off
	v_lshl_add_u64 v[206:207], s[30:31], 0, v[194:195]
	s_mov_b32 m0, s34
	s_nop 0
	global_load_lds_dwordx4 v[206:207], off
	v_lshl_add_u64 v[206:207], s[30:31], 0, v[198:199]
	s_add_i32 m0, s34, 0x2000
	s_nop 0
	global_load_lds_dwordx4 v[206:207], off
	v_lshl_add_u64 v[206:207], v[210:211], 0, s[12:13]
	s_mov_b32 m0, s46
	s_nop 0
	global_load_lds_dwordx4 v[206:207], off
	v_lshl_add_u64 v[206:207], v[212:213], 0, s[12:13]
	s_mov_b32 m0, s47
	s_nop 0
	global_load_lds_dwordx4 v[206:207], off
	ds_read_b128 v[160:163], v248 offset:49152
	ds_read_b128 v[164:167], v248 offset:50176
	ds_read_b128 v[168:171], v248 offset:51200
	ds_read_b128 v[172:175], v248 offset:52224
	ds_read_b128 v[176:179], v248 offset:53248
	ds_read_b128 v[180:183], v248 offset:54272
	ds_read_b128 v[184:187], v248 offset:55296
	ds_read_b128 v[188:191], v248 offset:56320
	s_waitcnt vmcnt(8)
	s_waitcnt lgkmcnt(0)
	s_setprio 1
	s_barrier
	v_mfma_f32_16x16x32_bf16 v[60:63], v[120:123], v[160:163], v[60:63]
	v_mfma_f32_16x16x32_bf16 v[56:59], v[128:131], v[160:163], v[56:59]
	v_mfma_f32_16x16x32_bf16 v[44:47], v[120:123], v[168:171], v[44:47]
	v_mfma_f32_16x16x32_bf16 v[40:43], v[128:131], v[168:171], v[40:43]
	v_mfma_f32_16x16x32_bf16 v[28:31], v[120:123], v[176:179], v[28:31]
	v_mfma_f32_16x16x32_bf16 v[24:27], v[128:131], v[176:179], v[24:27]
	v_mfma_f32_16x16x32_bf16 v[12:15], v[120:123], v[184:187], v[12:15]
	v_mfma_f32_16x16x32_bf16 v[8:11], v[128:131], v[184:187], v[8:11]
	v_mfma_f32_16x16x32_bf16 v[60:63], v[124:127], v[164:167], v[60:63]
	v_mfma_f32_16x16x32_bf16 v[56:59], v[132:135], v[164:167], v[56:59]
	v_mfma_f32_16x16x32_bf16 v[44:47], v[124:127], v[172:175], v[44:47]
	v_mfma_f32_16x16x32_bf16 v[40:43], v[132:135], v[172:175], v[40:43]
	v_mfma_f32_16x16x32_bf16 v[28:31], v[124:127], v[180:183], v[28:31]
	v_mfma_f32_16x16x32_bf16 v[24:27], v[132:135], v[180:183], v[24:27]
	v_mfma_f32_16x16x32_bf16 v[12:15], v[124:127], v[188:191], v[12:15]
	v_mfma_f32_16x16x32_bf16 v[8:11], v[132:135], v[188:191], v[8:11]
	s_setprio 0
	s_setprio 1
	v_mfma_f32_16x16x32_bf16 v[52:55], v[140:143], v[160:163], v[52:55]
	v_mfma_f32_16x16x32_bf16 v[48:51], v[152:155], v[160:163], v[48:51]
	v_mfma_f32_16x16x32_bf16 v[36:39], v[140:143], v[168:171], v[36:39]
	v_mfma_f32_16x16x32_bf16 v[32:35], v[152:155], v[168:171], v[32:35]
	v_mfma_f32_16x16x32_bf16 v[20:23], v[140:143], v[176:179], v[20:23]
	v_mfma_f32_16x16x32_bf16 v[16:19], v[152:155], v[176:179], v[16:19]
	v_mfma_f32_16x16x32_bf16 v[4:7], v[140:143], v[184:187], v[4:7]
	v_mfma_f32_16x16x32_bf16 v[0:3], v[152:155], v[184:187], v[0:3]
	v_mfma_f32_16x16x32_bf16 v[52:55], v[148:151], v[164:167], v[52:55]
	v_mfma_f32_16x16x32_bf16 v[48:51], v[156:159], v[164:167], v[48:51]
	v_mfma_f32_16x16x32_bf16 v[36:39], v[148:151], v[172:175], v[36:39]
	v_mfma_f32_16x16x32_bf16 v[32:35], v[156:159], v[172:175], v[32:35]
	v_mfma_f32_16x16x32_bf16 v[20:23], v[148:151], v[180:183], v[20:23]
	v_mfma_f32_16x16x32_bf16 v[16:19], v[156:159], v[180:183], v[16:19]
	v_mfma_f32_16x16x32_bf16 v[4:7], v[148:151], v[188:191], v[4:7]
	v_mfma_f32_16x16x32_bf16 v[0:3], v[156:159], v[188:191], v[0:3]
	s_barrier
	s_setprio 0
	s_add_i32 s64, s64, 2
	s_add_u32 s28, s28, 0x100
	s_addc_u32 s29, s29, 0
	s_add_u32 s62, s62, 0x100
	s_addc_u32 s63, s63, 0
	s_cmp_gt_u32 s64, 13
	s_cbranch_scc0 .LBB0_1109
	s_and_b64 vcc, exec, s[14:15]
	s_cbranch_vccz .LBB0_1112
	s_barrier
